# SCAN rewrite: 32 chunk loads in flight per lane instead of 2
# speedup vs baseline: 1.0009x; 1.0009x over previous
.LBB0_521:
.LBB0_522:
	v_lshrrev_b32_e32 v0, 11, v6
	v_and_b32_e32 v0, 12, v0
	s_getpc_b64 s[14:15]
	s_add_u32 s14, s14, _ZN2mk5DEC64E@rel32@lo+4
	s_addc_u32 s15, s15, _ZN2mk5DEC64E@rel32@hi+12
	global_load_dword v0, v0, s[14:15]
	v_lshlrev_b32_e32 v2, 1, v6
	v_bfe_u32 v1, v6, 13, 2
	v_ashrrev_i32_e32 v3, 15, v6
	v_and_b32_e32 v2, 0x3ffe, v2
	v_lshl_or_b32 v7, v3, 8, v1
	v_lshlrev_b32_e32 v8, 1, v2
	v_lshl_or_b32 v12, v7, 15, v8
	v_mov_b32_e32 v4, 0
	v_mov_b32_e32 v5, 0
	global_load_dword v20, v12, s[6:7]
	s_add_u32 s6, s6, 0x20000
	s_addc_u32 s7, s7, 0
	global_load_dword v21, v12, s[6:7]
	s_add_u32 s6, s6, 0x20000
	s_addc_u32 s7, s7, 0
	global_load_dword v22, v12, s[6:7]
	s_add_u32 s6, s6, 0x20000
	s_addc_u32 s7, s7, 0
	global_load_dword v23, v12, s[6:7]
	s_add_u32 s6, s6, 0x20000
	s_addc_u32 s7, s7, 0
	global_load_dword v24, v12, s[6:7]
	s_add_u32 s6, s6, 0x20000
	s_addc_u32 s7, s7, 0
	global_load_dword v25, v12, s[6:7]
	s_add_u32 s6, s6, 0x20000
	s_addc_u32 s7, s7, 0
	global_load_dword v26, v12, s[6:7]
	s_add_u32 s6, s6, 0x20000
	s_addc_u32 s7, s7, 0
	global_load_dword v27, v12, s[6:7]
	s_add_u32 s6, s6, 0x20000
	s_addc_u32 s7, s7, 0
	global_load_dword v28, v12, s[6:7]
	s_add_u32 s6, s6, 0x20000
	s_addc_u32 s7, s7, 0
	global_load_dword v29, v12, s[6:7]
	s_add_u32 s6, s6, 0x20000
	s_addc_u32 s7, s7, 0
	global_load_dword v30, v12, s[6:7]
	s_add_u32 s6, s6, 0x20000
	s_addc_u32 s7, s7, 0
	global_load_dword v31, v12, s[6:7]
	s_add_u32 s6, s6, 0x20000
	s_addc_u32 s7, s7, 0
	global_load_dword v32, v12, s[6:7]
	s_add_u32 s6, s6, 0x20000
	s_addc_u32 s7, s7, 0
	global_load_dword v33, v12, s[6:7]
	s_add_u32 s6, s6, 0x20000
	s_addc_u32 s7, s7, 0
	global_load_dword v34, v12, s[6:7]
	s_add_u32 s6, s6, 0x20000
	s_addc_u32 s7, s7, 0
	global_load_dword v35, v12, s[6:7]
	s_add_u32 s6, s6, 0x20000
	s_addc_u32 s7, s7, 0
	global_load_dword v36, v12, s[6:7]
	s_add_u32 s6, s6, 0x20000
	s_addc_u32 s7, s7, 0
	global_load_dword v37, v12, s[6:7]
	s_add_u32 s6, s6, 0x20000
	s_addc_u32 s7, s7, 0
	global_load_dword v38, v12, s[6:7]
	s_add_u32 s6, s6, 0x20000
	s_addc_u32 s7, s7, 0
	global_load_dword v39, v12, s[6:7]
	s_add_u32 s6, s6, 0x20000
	s_addc_u32 s7, s7, 0
	global_load_dword v40, v12, s[6:7]
	s_add_u32 s6, s6, 0x20000
	s_addc_u32 s7, s7, 0
	global_load_dword v41, v12, s[6:7]
	s_add_u32 s6, s6, 0x20000
	s_addc_u32 s7, s7, 0
	global_load_dword v42, v12, s[6:7]
	s_add_u32 s6, s6, 0x20000
	s_addc_u32 s7, s7, 0
	global_load_dword v43, v12, s[6:7]
	s_add_u32 s6, s6, 0x20000
	s_addc_u32 s7, s7, 0
	global_load_dword v44, v12, s[6:7]
	s_add_u32 s6, s6, 0x20000
	s_addc_u32 s7, s7, 0
	global_load_dword v45, v12, s[6:7]
	s_add_u32 s6, s6, 0x20000
	s_addc_u32 s7, s7, 0
	global_load_dword v46, v12, s[6:7]
	s_add_u32 s6, s6, 0x20000
	s_addc_u32 s7, s7, 0
	global_load_dword v47, v12, s[6:7]
	s_add_u32 s6, s6, 0x20000
	s_addc_u32 s7, s7, 0
	global_load_dword v48, v12, s[6:7]
	s_add_u32 s6, s6, 0x20000
	s_addc_u32 s7, s7, 0
	global_load_dword v49, v12, s[6:7]
	s_add_u32 s6, s6, 0x20000
	s_addc_u32 s7, s7, 0
	global_load_dword v50, v12, s[6:7]
	s_add_u32 s6, s6, 0x20000
	s_addc_u32 s7, s7, 0
	global_load_dword v51, v12, s[6:7]
	s_add_u32 s6, s6, 0x20000
	s_addc_u32 s7, s7, 0
	s_waitcnt vmcnt(32)
	v_mov_b32_e32 v1, v0
	s_waitcnt vmcnt(31)
	v_cvt_pk_bf16_f32 v84, v4, v5
	v_lshlrev_b32_e32 v16, 16, v20
	v_and_b32_e32 v17, 0xffff0000, v20
	global_store_dword v12, v84, s[10:11]
	s_add_u32 s10, s10, 0x20000
	s_addc_u32 s11, s11, 0
	v_pk_fma_f32 v[4:5], v[0:1], v[4:5], v[16:17]
	global_load_dword v20, v12, s[6:7]
	s_add_u32 s6, s6, 0x20000
	s_addc_u32 s7, s7, 0
	s_waitcnt vmcnt(32)
	v_cvt_pk_bf16_f32 v85, v4, v5
	v_lshlrev_b32_e32 v16, 16, v21
	v_and_b32_e32 v17, 0xffff0000, v21
	global_store_dword v12, v85, s[10:11]
	s_add_u32 s10, s10, 0x20000
	s_addc_u32 s11, s11, 0
	v_pk_fma_f32 v[4:5], v[0:1], v[4:5], v[16:17]
	global_load_dword v21, v12, s[6:7]
	s_add_u32 s6, s6, 0x20000
	s_addc_u32 s7, s7, 0
	s_waitcnt vmcnt(33)
	v_cvt_pk_bf16_f32 v86, v4, v5
	v_lshlrev_b32_e32 v16, 16, v22
	v_and_b32_e32 v17, 0xffff0000, v22
	global_store_dword v12, v86, s[10:11]
	s_add_u32 s10, s10, 0x20000
	s_addc_u32 s11, s11, 0
	v_pk_fma_f32 v[4:5], v[0:1], v[4:5], v[16:17]
	global_load_dword v22, v12, s[6:7]
	s_add_u32 s6, s6, 0x20000
	s_addc_u32 s7, s7, 0
	s_waitcnt vmcnt(34)
	v_cvt_pk_bf16_f32 v87, v4, v5
	v_lshlrev_b32_e32 v16, 16, v23
	v_and_b32_e32 v17, 0xffff0000, v23
	global_store_dword v12, v87, s[10:11]
	s_add_u32 s10, s10, 0x20000
	s_addc_u32 s11, s11, 0
	v_pk_fma_f32 v[4:5], v[0:1], v[4:5], v[16:17]
	global_load_dword v23, v12, s[6:7]
	s_add_u32 s6, s6, 0x20000
	s_addc_u32 s7, s7, 0
	s_waitcnt vmcnt(35)
	v_cvt_pk_bf16_f32 v88, v4, v5
	v_lshlrev_b32_e32 v16, 16, v24
	v_and_b32_e32 v17, 0xffff0000, v24
	global_store_dword v12, v88, s[10:11]
	s_add_u32 s10, s10, 0x20000
	s_addc_u32 s11, s11, 0
	v_pk_fma_f32 v[4:5], v[0:1], v[4:5], v[16:17]
	global_load_dword v24, v12, s[6:7]
	s_add_u32 s6, s6, 0x20000
	s_addc_u32 s7, s7, 0
	s_waitcnt vmcnt(36)
	v_cvt_pk_bf16_f32 v89, v4, v5
	v_lshlrev_b32_e32 v16, 16, v25
	v_and_b32_e32 v17, 0xffff0000, v25
	global_store_dword v12, v89, s[10:11]
	s_add_u32 s10, s10, 0x20000
	s_addc_u32 s11, s11, 0
	v_pk_fma_f32 v[4:5], v[0:1], v[4:5], v[16:17]
	global_load_dword v25, v12, s[6:7]
	s_add_u32 s6, s6, 0x20000
	s_addc_u32 s7, s7, 0
	s_waitcnt vmcnt(37)
	v_cvt_pk_bf16_f32 v90, v4, v5
	v_lshlrev_b32_e32 v16, 16, v26
	v_and_b32_e32 v17, 0xffff0000, v26
	global_store_dword v12, v90, s[10:11]
	s_add_u32 s10, s10, 0x20000
	s_addc_u32 s11, s11, 0
	v_pk_fma_f32 v[4:5], v[0:1], v[4:5], v[16:17]
	global_load_dword v26, v12, s[6:7]
	s_add_u32 s6, s6, 0x20000
	s_addc_u32 s7, s7, 0
	s_waitcnt vmcnt(38)
	v_cvt_pk_bf16_f32 v91, v4, v5
	v_lshlrev_b32_e32 v16, 16, v27
	v_and_b32_e32 v17, 0xffff0000, v27
	global_store_dword v12, v91, s[10:11]
	s_add_u32 s10, s10, 0x20000
	s_addc_u32 s11, s11, 0
	v_pk_fma_f32 v[4:5], v[0:1], v[4:5], v[16:17]
	global_load_dword v27, v12, s[6:7]
	s_add_u32 s6, s6, 0x20000
	s_addc_u32 s7, s7, 0
	s_waitcnt vmcnt(39)
	v_cvt_pk_bf16_f32 v92, v4, v5
	v_lshlrev_b32_e32 v16, 16, v28
	v_and_b32_e32 v17, 0xffff0000, v28
	global_store_dword v12, v92, s[10:11]
	s_add_u32 s10, s10, 0x20000
	s_addc_u32 s11, s11, 0
	v_pk_fma_f32 v[4:5], v[0:1], v[4:5], v[16:17]
	global_load_dword v28, v12, s[6:7]
	s_add_u32 s6, s6, 0x20000
	s_addc_u32 s7, s7, 0
	s_waitcnt vmcnt(40)
	v_cvt_pk_bf16_f32 v93, v4, v5
	v_lshlrev_b32_e32 v16, 16, v29
	v_and_b32_e32 v17, 0xffff0000, v29
	global_store_dword v12, v93, s[10:11]
	s_add_u32 s10, s10, 0x20000
	s_addc_u32 s11, s11, 0
	v_pk_fma_f32 v[4:5], v[0:1], v[4:5], v[16:17]
	global_load_dword v29, v12, s[6:7]
	s_add_u32 s6, s6, 0x20000
	s_addc_u32 s7, s7, 0
	s_waitcnt vmcnt(41)
	v_cvt_pk_bf16_f32 v94, v4, v5
	v_lshlrev_b32_e32 v16, 16, v30
	v_and_b32_e32 v17, 0xffff0000, v30
	global_store_dword v12, v94, s[10:11]
	s_add_u32 s10, s10, 0x20000
	s_addc_u32 s11, s11, 0
	v_pk_fma_f32 v[4:5], v[0:1], v[4:5], v[16:17]
	global_load_dword v30, v12, s[6:7]
	s_add_u32 s6, s6, 0x20000
	s_addc_u32 s7, s7, 0
	s_waitcnt vmcnt(42)
	v_cvt_pk_bf16_f32 v95, v4, v5
	v_lshlrev_b32_e32 v16, 16, v31
	v_and_b32_e32 v17, 0xffff0000, v31
	global_store_dword v12, v95, s[10:11]
	s_add_u32 s10, s10, 0x20000
	s_addc_u32 s11, s11, 0
	v_pk_fma_f32 v[4:5], v[0:1], v[4:5], v[16:17]
	global_load_dword v31, v12, s[6:7]
	s_add_u32 s6, s6, 0x20000
	s_addc_u32 s7, s7, 0
	s_waitcnt vmcnt(43)
	v_cvt_pk_bf16_f32 v96, v4, v5
	v_lshlrev_b32_e32 v16, 16, v32
	v_and_b32_e32 v17, 0xffff0000, v32
	global_store_dword v12, v96, s[10:11]
	s_add_u32 s10, s10, 0x20000
	s_addc_u32 s11, s11, 0
	v_pk_fma_f32 v[4:5], v[0:1], v[4:5], v[16:17]
	global_load_dword v32, v12, s[6:7]
	s_add_u32 s6, s6, 0x20000
	s_addc_u32 s7, s7, 0
	s_waitcnt vmcnt(44)
	v_cvt_pk_bf16_f32 v97, v4, v5
	v_lshlrev_b32_e32 v16, 16, v33
	v_and_b32_e32 v17, 0xffff0000, v33
	global_store_dword v12, v97, s[10:11]
	s_add_u32 s10, s10, 0x20000
	s_addc_u32 s11, s11, 0
	v_pk_fma_f32 v[4:5], v[0:1], v[4:5], v[16:17]
	global_load_dword v33, v12, s[6:7]
	s_add_u32 s6, s6, 0x20000
	s_addc_u32 s7, s7, 0
	s_waitcnt vmcnt(45)
	v_cvt_pk_bf16_f32 v98, v4, v5
	v_lshlrev_b32_e32 v16, 16, v34
	v_and_b32_e32 v17, 0xffff0000, v34
	global_store_dword v12, v98, s[10:11]
	s_add_u32 s10, s10, 0x20000
	s_addc_u32 s11, s11, 0
	v_pk_fma_f32 v[4:5], v[0:1], v[4:5], v[16:17]
	global_load_dword v34, v12, s[6:7]
	s_add_u32 s6, s6, 0x20000
	s_addc_u32 s7, s7, 0
	s_waitcnt vmcnt(46)
	v_cvt_pk_bf16_f32 v99, v4, v5
	v_lshlrev_b32_e32 v16, 16, v35
	v_and_b32_e32 v17, 0xffff0000, v35
	global_store_dword v12, v99, s[10:11]
	s_add_u32 s10, s10, 0x20000
	s_addc_u32 s11, s11, 0
	v_pk_fma_f32 v[4:5], v[0:1], v[4:5], v[16:17]
	global_load_dword v35, v12, s[6:7]
	s_add_u32 s6, s6, 0x20000
	s_addc_u32 s7, s7, 0
	s_waitcnt vmcnt(47)
	v_cvt_pk_bf16_f32 v100, v4, v5
	v_lshlrev_b32_e32 v16, 16, v36
	v_and_b32_e32 v17, 0xffff0000, v36
	global_store_dword v12, v100, s[10:11]
	s_add_u32 s10, s10, 0x20000
	s_addc_u32 s11, s11, 0
	v_pk_fma_f32 v[4:5], v[0:1], v[4:5], v[16:17]
	global_load_dword v36, v12, s[6:7]
	s_add_u32 s6, s6, 0x20000
	s_addc_u32 s7, s7, 0
	s_waitcnt vmcnt(48)
	v_cvt_pk_bf16_f32 v101, v4, v5
	v_lshlrev_b32_e32 v16, 16, v37
	v_and_b32_e32 v17, 0xffff0000, v37
	global_store_dword v12, v101, s[10:11]
	s_add_u32 s10, s10, 0x20000
	s_addc_u32 s11, s11, 0
	v_pk_fma_f32 v[4:5], v[0:1], v[4:5], v[16:17]
	global_load_dword v37, v12, s[6:7]
	s_add_u32 s6, s6, 0x20000
	s_addc_u32 s7, s7, 0
	s_waitcnt vmcnt(49)
	v_cvt_pk_bf16_f32 v102, v4, v5
	v_lshlrev_b32_e32 v16, 16, v38
	v_and_b32_e32 v17, 0xffff0000, v38
	global_store_dword v12, v102, s[10:11]
	s_add_u32 s10, s10, 0x20000
	s_addc_u32 s11, s11, 0
	v_pk_fma_f32 v[4:5], v[0:1], v[4:5], v[16:17]
	global_load_dword v38, v12, s[6:7]
	s_add_u32 s6, s6, 0x20000
	s_addc_u32 s7, s7, 0
	s_waitcnt vmcnt(50)
	v_cvt_pk_bf16_f32 v103, v4, v5
	v_lshlrev_b32_e32 v16, 16, v39
	v_and_b32_e32 v17, 0xffff0000, v39
	global_store_dword v12, v103, s[10:11]
	s_add_u32 s10, s10, 0x20000
	s_addc_u32 s11, s11, 0
	v_pk_fma_f32 v[4:5], v[0:1], v[4:5], v[16:17]
	global_load_dword v39, v12, s[6:7]
	s_add_u32 s6, s6, 0x20000
	s_addc_u32 s7, s7, 0
	s_waitcnt vmcnt(51)
	v_cvt_pk_bf16_f32 v104, v4, v5
	v_lshlrev_b32_e32 v16, 16, v40
	v_and_b32_e32 v17, 0xffff0000, v40
	global_store_dword v12, v104, s[10:11]
	s_add_u32 s10, s10, 0x20000
	s_addc_u32 s11, s11, 0
	v_pk_fma_f32 v[4:5], v[0:1], v[4:5], v[16:17]
	global_load_dword v40, v12, s[6:7]
	s_add_u32 s6, s6, 0x20000
	s_addc_u32 s7, s7, 0
	s_waitcnt vmcnt(52)
	v_cvt_pk_bf16_f32 v105, v4, v5
	v_lshlrev_b32_e32 v16, 16, v41
	v_and_b32_e32 v17, 0xffff0000, v41
	global_store_dword v12, v105, s[10:11]
	s_add_u32 s10, s10, 0x20000
	s_addc_u32 s11, s11, 0
	v_pk_fma_f32 v[4:5], v[0:1], v[4:5], v[16:17]
	global_load_dword v41, v12, s[6:7]
	s_add_u32 s6, s6, 0x20000
	s_addc_u32 s7, s7, 0
	s_waitcnt vmcnt(53)
	v_cvt_pk_bf16_f32 v106, v4, v5
	v_lshlrev_b32_e32 v16, 16, v42
	v_and_b32_e32 v17, 0xffff0000, v42
	global_store_dword v12, v106, s[10:11]
	s_add_u32 s10, s10, 0x20000
	s_addc_u32 s11, s11, 0
	v_pk_fma_f32 v[4:5], v[0:1], v[4:5], v[16:17]
	global_load_dword v42, v12, s[6:7]
	s_add_u32 s6, s6, 0x20000
	s_addc_u32 s7, s7, 0
	s_waitcnt vmcnt(54)
	v_cvt_pk_bf16_f32 v107, v4, v5
	v_lshlrev_b32_e32 v16, 16, v43
	v_and_b32_e32 v17, 0xffff0000, v43
	global_store_dword v12, v107, s[10:11]
	s_add_u32 s10, s10, 0x20000
	s_addc_u32 s11, s11, 0
	v_pk_fma_f32 v[4:5], v[0:1], v[4:5], v[16:17]
	global_load_dword v43, v12, s[6:7]
	s_add_u32 s6, s6, 0x20000
	s_addc_u32 s7, s7, 0
	s_waitcnt vmcnt(55)
	v_cvt_pk_bf16_f32 v108, v4, v5
	v_lshlrev_b32_e32 v16, 16, v44
	v_and_b32_e32 v17, 0xffff0000, v44
	global_store_dword v12, v108, s[10:11]
	s_add_u32 s10, s10, 0x20000
	s_addc_u32 s11, s11, 0
	v_pk_fma_f32 v[4:5], v[0:1], v[4:5], v[16:17]
	global_load_dword v44, v12, s[6:7]
	s_add_u32 s6, s6, 0x20000
	s_addc_u32 s7, s7, 0
	s_waitcnt vmcnt(56)
	v_cvt_pk_bf16_f32 v109, v4, v5
	v_lshlrev_b32_e32 v16, 16, v45
	v_and_b32_e32 v17, 0xffff0000, v45
	global_store_dword v12, v109, s[10:11]
	s_add_u32 s10, s10, 0x20000
	s_addc_u32 s11, s11, 0
	v_pk_fma_f32 v[4:5], v[0:1], v[4:5], v[16:17]
	global_load_dword v45, v12, s[6:7]
	s_add_u32 s6, s6, 0x20000
	s_addc_u32 s7, s7, 0
	s_waitcnt vmcnt(57)
	v_cvt_pk_bf16_f32 v110, v4, v5
	v_lshlrev_b32_e32 v16, 16, v46
	v_and_b32_e32 v17, 0xffff0000, v46
	global_store_dword v12, v110, s[10:11]
	s_add_u32 s10, s10, 0x20000
	s_addc_u32 s11, s11, 0
	v_pk_fma_f32 v[4:5], v[0:1], v[4:5], v[16:17]
	global_load_dword v46, v12, s[6:7]
	s_add_u32 s6, s6, 0x20000
	s_addc_u32 s7, s7, 0
	s_waitcnt vmcnt(58)
	v_cvt_pk_bf16_f32 v111, v4, v5
	v_lshlrev_b32_e32 v16, 16, v47
	v_and_b32_e32 v17, 0xffff0000, v47
	global_store_dword v12, v111, s[10:11]
	s_add_u32 s10, s10, 0x20000
	s_addc_u32 s11, s11, 0
	v_pk_fma_f32 v[4:5], v[0:1], v[4:5], v[16:17]
	global_load_dword v47, v12, s[6:7]
	s_add_u32 s6, s6, 0x20000
	s_addc_u32 s7, s7, 0
	s_waitcnt vmcnt(59)
	v_cvt_pk_bf16_f32 v112, v4, v5
	v_lshlrev_b32_e32 v16, 16, v48
	v_and_b32_e32 v17, 0xffff0000, v48
	global_store_dword v12, v112, s[10:11]
	s_add_u32 s10, s10, 0x20000
	s_addc_u32 s11, s11, 0
	v_pk_fma_f32 v[4:5], v[0:1], v[4:5], v[16:17]
	global_load_dword v48, v12, s[6:7]
	s_add_u32 s6, s6, 0x20000
	s_addc_u32 s7, s7, 0
	s_waitcnt vmcnt(60)
	v_cvt_pk_bf16_f32 v113, v4, v5
	v_lshlrev_b32_e32 v16, 16, v49
	v_and_b32_e32 v17, 0xffff0000, v49
	global_store_dword v12, v113, s[10:11]
	s_add_u32 s10, s10, 0x20000
	s_addc_u32 s11, s11, 0
	v_pk_fma_f32 v[4:5], v[0:1], v[4:5], v[16:17]
	global_load_dword v49, v12, s[6:7]
	s_add_u32 s6, s6, 0x20000
	s_addc_u32 s7, s7, 0
	s_waitcnt vmcnt(61)
	v_cvt_pk_bf16_f32 v114, v4, v5
	v_lshlrev_b32_e32 v16, 16, v50
	v_and_b32_e32 v17, 0xffff0000, v50
	global_store_dword v12, v114, s[10:11]
	s_add_u32 s10, s10, 0x20000
	s_addc_u32 s11, s11, 0
	v_pk_fma_f32 v[4:5], v[0:1], v[4:5], v[16:17]
	global_load_dword v50, v12, s[6:7]
	s_add_u32 s6, s6, 0x20000
	s_addc_u32 s7, s7, 0
	s_waitcnt vmcnt(62)
	v_cvt_pk_bf16_f32 v115, v4, v5
	v_lshlrev_b32_e32 v16, 16, v51
	v_and_b32_e32 v17, 0xffff0000, v51
	global_store_dword v12, v115, s[10:11]
	s_add_u32 s10, s10, 0x20000
	s_addc_u32 s11, s11, 0
	v_pk_fma_f32 v[4:5], v[0:1], v[4:5], v[16:17]
	global_load_dword v51, v12, s[6:7]
	s_add_u32 s6, s6, 0x20000
	s_addc_u32 s7, s7, 0
	s_waitcnt vmcnt(62)
	v_cvt_pk_bf16_f32 v116, v4, v5
	v_lshlrev_b32_e32 v16, 16, v20
	v_and_b32_e32 v17, 0xffff0000, v20
	global_store_dword v12, v116, s[10:11]
	s_add_u32 s10, s10, 0x20000
	s_addc_u32 s11, s11, 0
	v_pk_fma_f32 v[4:5], v[0:1], v[4:5], v[16:17]
	s_waitcnt vmcnt(61)
	v_cvt_pk_bf16_f32 v117, v4, v5
	v_lshlrev_b32_e32 v16, 16, v21
	v_and_b32_e32 v17, 0xffff0000, v21
	global_store_dword v12, v117, s[10:11]
	s_add_u32 s10, s10, 0x20000
	s_addc_u32 s11, s11, 0
	v_pk_fma_f32 v[4:5], v[0:1], v[4:5], v[16:17]
	s_waitcnt vmcnt(60)
	v_cvt_pk_bf16_f32 v118, v4, v5
	v_lshlrev_b32_e32 v16, 16, v22
	v_and_b32_e32 v17, 0xffff0000, v22
	global_store_dword v12, v118, s[10:11]
	s_add_u32 s10, s10, 0x20000
	s_addc_u32 s11, s11, 0
	v_pk_fma_f32 v[4:5], v[0:1], v[4:5], v[16:17]
	s_waitcnt vmcnt(59)
	v_cvt_pk_bf16_f32 v119, v4, v5
	v_lshlrev_b32_e32 v16, 16, v23
	v_and_b32_e32 v17, 0xffff0000, v23
	global_store_dword v12, v119, s[10:11]
	s_add_u32 s10, s10, 0x20000
	s_addc_u32 s11, s11, 0
	v_pk_fma_f32 v[4:5], v[0:1], v[4:5], v[16:17]
	s_waitcnt vmcnt(58)
	v_cvt_pk_bf16_f32 v120, v4, v5
	v_lshlrev_b32_e32 v16, 16, v24
	v_and_b32_e32 v17, 0xffff0000, v24
	global_store_dword v12, v120, s[10:11]
	s_add_u32 s10, s10, 0x20000
	s_addc_u32 s11, s11, 0
	v_pk_fma_f32 v[4:5], v[0:1], v[4:5], v[16:17]
	s_waitcnt vmcnt(57)
	v_cvt_pk_bf16_f32 v121, v4, v5
	v_lshlrev_b32_e32 v16, 16, v25
	v_and_b32_e32 v17, 0xffff0000, v25
	global_store_dword v12, v121, s[10:11]
	s_add_u32 s10, s10, 0x20000
	s_addc_u32 s11, s11, 0
	v_pk_fma_f32 v[4:5], v[0:1], v[4:5], v[16:17]
	s_waitcnt vmcnt(56)
	v_cvt_pk_bf16_f32 v122, v4, v5
	v_lshlrev_b32_e32 v16, 16, v26
	v_and_b32_e32 v17, 0xffff0000, v26
	global_store_dword v12, v122, s[10:11]
	s_add_u32 s10, s10, 0x20000
	s_addc_u32 s11, s11, 0
	v_pk_fma_f32 v[4:5], v[0:1], v[4:5], v[16:17]
	s_waitcnt vmcnt(55)
	v_cvt_pk_bf16_f32 v123, v4, v5
	v_lshlrev_b32_e32 v16, 16, v27
	v_and_b32_e32 v17, 0xffff0000, v27
	global_store_dword v12, v123, s[10:11]
	s_add_u32 s10, s10, 0x20000
	s_addc_u32 s11, s11, 0
	v_pk_fma_f32 v[4:5], v[0:1], v[4:5], v[16:17]
	s_waitcnt vmcnt(54)
	v_cvt_pk_bf16_f32 v124, v4, v5
	v_lshlrev_b32_e32 v16, 16, v28
	v_and_b32_e32 v17, 0xffff0000, v28
	global_store_dword v12, v124, s[10:11]
	s_add_u32 s10, s10, 0x20000
	s_addc_u32 s11, s11, 0
	v_pk_fma_f32 v[4:5], v[0:1], v[4:5], v[16:17]
	s_waitcnt vmcnt(53)
	v_cvt_pk_bf16_f32 v125, v4, v5
	v_lshlrev_b32_e32 v16, 16, v29
	v_and_b32_e32 v17, 0xffff0000, v29
	global_store_dword v12, v125, s[10:11]
	s_add_u32 s10, s10, 0x20000
	s_addc_u32 s11, s11, 0
	v_pk_fma_f32 v[4:5], v[0:1], v[4:5], v[16:17]
	s_waitcnt vmcnt(52)
	v_cvt_pk_bf16_f32 v126, v4, v5
	v_lshlrev_b32_e32 v16, 16, v30
	v_and_b32_e32 v17, 0xffff0000, v30
	global_store_dword v12, v126, s[10:11]
	s_add_u32 s10, s10, 0x20000
	s_addc_u32 s11, s11, 0
	v_pk_fma_f32 v[4:5], v[0:1], v[4:5], v[16:17]
	s_waitcnt vmcnt(51)
	v_cvt_pk_bf16_f32 v127, v4, v5
	v_lshlrev_b32_e32 v16, 16, v31
	v_and_b32_e32 v17, 0xffff0000, v31
	global_store_dword v12, v127, s[10:11]
	s_add_u32 s10, s10, 0x20000
	s_addc_u32 s11, s11, 0
	v_pk_fma_f32 v[4:5], v[0:1], v[4:5], v[16:17]
	s_waitcnt vmcnt(50)
	v_cvt_pk_bf16_f32 v128, v4, v5
	v_lshlrev_b32_e32 v16, 16, v32
	v_and_b32_e32 v17, 0xffff0000, v32
	global_store_dword v12, v128, s[10:11]
	s_add_u32 s10, s10, 0x20000
	s_addc_u32 s11, s11, 0
	v_pk_fma_f32 v[4:5], v[0:1], v[4:5], v[16:17]
	s_waitcnt vmcnt(49)
	v_cvt_pk_bf16_f32 v129, v4, v5
	v_lshlrev_b32_e32 v16, 16, v33
	v_and_b32_e32 v17, 0xffff0000, v33
	global_store_dword v12, v129, s[10:11]
	s_add_u32 s10, s10, 0x20000
	s_addc_u32 s11, s11, 0
	v_pk_fma_f32 v[4:5], v[0:1], v[4:5], v[16:17]
	s_waitcnt vmcnt(48)
	v_cvt_pk_bf16_f32 v130, v4, v5
	v_lshlrev_b32_e32 v16, 16, v34
	v_and_b32_e32 v17, 0xffff0000, v34
	global_store_dword v12, v130, s[10:11]
	s_add_u32 s10, s10, 0x20000
	s_addc_u32 s11, s11, 0
	v_pk_fma_f32 v[4:5], v[0:1], v[4:5], v[16:17]
	s_waitcnt vmcnt(47)
	v_cvt_pk_bf16_f32 v131, v4, v5
	v_lshlrev_b32_e32 v16, 16, v35
	v_and_b32_e32 v17, 0xffff0000, v35
	global_store_dword v12, v131, s[10:11]
	s_add_u32 s10, s10, 0x20000
	s_addc_u32 s11, s11, 0
	v_pk_fma_f32 v[4:5], v[0:1], v[4:5], v[16:17]
	s_waitcnt vmcnt(46)
	v_cvt_pk_bf16_f32 v132, v4, v5
	v_lshlrev_b32_e32 v16, 16, v36
	v_and_b32_e32 v17, 0xffff0000, v36
	global_store_dword v12, v132, s[10:11]
	s_add_u32 s10, s10, 0x20000
	s_addc_u32 s11, s11, 0
	v_pk_fma_f32 v[4:5], v[0:1], v[4:5], v[16:17]
	s_waitcnt vmcnt(45)
	v_cvt_pk_bf16_f32 v133, v4, v5
	v_lshlrev_b32_e32 v16, 16, v37
	v_and_b32_e32 v17, 0xffff0000, v37
	global_store_dword v12, v133, s[10:11]
	s_add_u32 s10, s10, 0x20000
	s_addc_u32 s11, s11, 0
	v_pk_fma_f32 v[4:5], v[0:1], v[4:5], v[16:17]
	s_waitcnt vmcnt(44)
	v_cvt_pk_bf16_f32 v134, v4, v5
	v_lshlrev_b32_e32 v16, 16, v38
	v_and_b32_e32 v17, 0xffff0000, v38
	global_store_dword v12, v134, s[10:11]
	s_add_u32 s10, s10, 0x20000
	s_addc_u32 s11, s11, 0
	v_pk_fma_f32 v[4:5], v[0:1], v[4:5], v[16:17]
	s_waitcnt vmcnt(43)
	v_cvt_pk_bf16_f32 v135, v4, v5
	v_lshlrev_b32_e32 v16, 16, v39
	v_and_b32_e32 v17, 0xffff0000, v39
	global_store_dword v12, v135, s[10:11]
	s_add_u32 s10, s10, 0x20000
	s_addc_u32 s11, s11, 0
	v_pk_fma_f32 v[4:5], v[0:1], v[4:5], v[16:17]
	s_waitcnt vmcnt(42)
	v_cvt_pk_bf16_f32 v136, v4, v5
	v_lshlrev_b32_e32 v16, 16, v40
	v_and_b32_e32 v17, 0xffff0000, v40
	global_store_dword v12, v136, s[10:11]
	s_add_u32 s10, s10, 0x20000
	s_addc_u32 s11, s11, 0
	v_pk_fma_f32 v[4:5], v[0:1], v[4:5], v[16:17]
	s_waitcnt vmcnt(41)
	v_cvt_pk_bf16_f32 v137, v4, v5
	v_lshlrev_b32_e32 v16, 16, v41
	v_and_b32_e32 v17, 0xffff0000, v41
	global_store_dword v12, v137, s[10:11]
	s_add_u32 s10, s10, 0x20000
	s_addc_u32 s11, s11, 0
	v_pk_fma_f32 v[4:5], v[0:1], v[4:5], v[16:17]
	s_waitcnt vmcnt(40)
	v_cvt_pk_bf16_f32 v138, v4, v5
	v_lshlrev_b32_e32 v16, 16, v42
	v_and_b32_e32 v17, 0xffff0000, v42
	global_store_dword v12, v138, s[10:11]
	s_add_u32 s10, s10, 0x20000
	s_addc_u32 s11, s11, 0
	v_pk_fma_f32 v[4:5], v[0:1], v[4:5], v[16:17]
	s_waitcnt vmcnt(39)
	v_cvt_pk_bf16_f32 v139, v4, v5
	v_lshlrev_b32_e32 v16, 16, v43
	v_and_b32_e32 v17, 0xffff0000, v43
	global_store_dword v12, v139, s[10:11]
	s_add_u32 s10, s10, 0x20000
	s_addc_u32 s11, s11, 0
	v_pk_fma_f32 v[4:5], v[0:1], v[4:5], v[16:17]
	s_waitcnt vmcnt(38)
	v_cvt_pk_bf16_f32 v140, v4, v5
	v_lshlrev_b32_e32 v16, 16, v44
	v_and_b32_e32 v17, 0xffff0000, v44
	global_store_dword v12, v140, s[10:11]
	s_add_u32 s10, s10, 0x20000
	s_addc_u32 s11, s11, 0
	v_pk_fma_f32 v[4:5], v[0:1], v[4:5], v[16:17]
	s_waitcnt vmcnt(37)
	v_cvt_pk_bf16_f32 v141, v4, v5
	v_lshlrev_b32_e32 v16, 16, v45
	v_and_b32_e32 v17, 0xffff0000, v45
	global_store_dword v12, v141, s[10:11]
	s_add_u32 s10, s10, 0x20000
	s_addc_u32 s11, s11, 0
	v_pk_fma_f32 v[4:5], v[0:1], v[4:5], v[16:17]
	s_waitcnt vmcnt(36)
	v_cvt_pk_bf16_f32 v142, v4, v5
	v_lshlrev_b32_e32 v16, 16, v46
	v_and_b32_e32 v17, 0xffff0000, v46
	global_store_dword v12, v142, s[10:11]
	s_add_u32 s10, s10, 0x20000
	s_addc_u32 s11, s11, 0
	v_pk_fma_f32 v[4:5], v[0:1], v[4:5], v[16:17]
	s_waitcnt vmcnt(35)
	v_cvt_pk_bf16_f32 v143, v4, v5
	v_lshlrev_b32_e32 v16, 16, v47
	v_and_b32_e32 v17, 0xffff0000, v47
	global_store_dword v12, v143, s[10:11]
	s_add_u32 s10, s10, 0x20000
	s_addc_u32 s11, s11, 0
	v_pk_fma_f32 v[4:5], v[0:1], v[4:5], v[16:17]
	s_waitcnt vmcnt(34)
	v_cvt_pk_bf16_f32 v144, v4, v5
	v_lshlrev_b32_e32 v16, 16, v48
	v_and_b32_e32 v17, 0xffff0000, v48
	global_store_dword v12, v144, s[10:11]
	s_add_u32 s10, s10, 0x20000
	s_addc_u32 s11, s11, 0
	v_pk_fma_f32 v[4:5], v[0:1], v[4:5], v[16:17]
	s_waitcnt vmcnt(33)
	v_cvt_pk_bf16_f32 v145, v4, v5
	v_lshlrev_b32_e32 v16, 16, v49
	v_and_b32_e32 v17, 0xffff0000, v49
	global_store_dword v12, v145, s[10:11]
	s_add_u32 s10, s10, 0x20000
	s_addc_u32 s11, s11, 0
	v_pk_fma_f32 v[4:5], v[0:1], v[4:5], v[16:17]
	s_waitcnt vmcnt(32)
	v_cvt_pk_bf16_f32 v146, v4, v5
	v_lshlrev_b32_e32 v16, 16, v50
	v_and_b32_e32 v17, 0xffff0000, v50
	global_store_dword v12, v146, s[10:11]
	s_add_u32 s10, s10, 0x20000
	s_addc_u32 s11, s11, 0
	v_pk_fma_f32 v[4:5], v[0:1], v[4:5], v[16:17]
	s_waitcnt vmcnt(31)
	v_cvt_pk_bf16_f32 v147, v4, v5
	v_lshlrev_b32_e32 v16, 16, v51
	v_and_b32_e32 v17, 0xffff0000, v51
	global_store_dword v12, v147, s[10:11]
	s_add_u32 s10, s10, 0x20000
	s_addc_u32 s11, s11, 0
	v_pk_fma_f32 v[4:5], v[0:1], v[4:5], v[16:17]

.LBB0_580:
	s_or_b64 exec, exec, s[4:5]
	v_add_u32_e32 v0, s7, v93
	v_mov_b64_e32 v[2:3], s[12:13]
	v_mad_i64_i32 v[2:3], s[4:5], v0, s85, v[2:3]
	s_lshl_b32 s26, s16, 1
	v_lshl_add_u64 v[2:3], v[2:3], 0, s[26:27]
	v_mov_b32_e32 v87, v169
	v_lshl_add_u64 v[24:25], v[2:3], 0, v[86:87]
	v_add_co_u32_e64 v2, s[4:5], s86, v24
	s_waitcnt vmcnt(0) lgkmcnt(0)
	s_barrier
	s_nop 0
	v_addc_co_u32_e64 v3, s[4:5], 0, v25, s[4:5]
	global_load_dwordx2 v[20:21], v[2:3], off offset:2048
	s_waitcnt lgkmcnt(0)
	v_ashrrev_i32_e32 v1, 31, v0
	v_lshlrev_b64 v[0:1], 11, v[0:1]
	v_lshl_add_u64 v[0:1], s[10:11], 0, v[0:1]
	v_lshl_add_u64 v[28:29], v[0:1], 0, s[26:27]
	s_lshl_b32 s26, s16, 2
	v_lshl_add_u64 v[8:9], v[82:83], 0, s[26:27]
	global_load_dwordx4 v[0:3], v[8:9], off
	v_add_u32_e32 v22, s14, v88
	ds_read2st64_b32 v[22:23], v22 offset0:204 offset1:205
	ds_read_b32 v34, v96 offset:52224
	ds_read_b32 v35, v97 offset:52224
	s_mov_b64 s[4:5], 0x1800
	v_lshl_add_u64 v[26:27], v[24:25], 0, s[4:5]
	v_lshl_add_u64 v[24:25], v[28:29], 0, v[86:87]
	global_load_dwordx2 v[30:31], v[26:27], off offset:16
	global_load_dwordx2 v[28:29], v[26:27], off offset:48
	s_waitcnt lgkmcnt(0)
	v_pk_add_f32 v[22:23], v[22:23], v[34:35]
	s_mov_b32 s7, 0xf700000
	v_add_f32_e32 v22, v22, v23
	v_fmamk_f32 v22, v22, 0x3c000000, v226
	v_rsq_f32_e32 v22, v22
	v_add_co_u32_e64 v34, s[4:5], s7, v24
	s_add_i32 s6, s6, s24
	v_pk_mul_f32 v[32:33], v[32:33], v[22:23] op_sel_hi:[1,0]
	v_pk_mul_f32 v[18:19], v[18:19], v[22:23] op_sel_hi:[1,0]
	v_addc_co_u32_e64 v35, s[4:5], 0, v25, s[4:5]
	s_mov_b64 s[4:5], 0xf700400
	s_add_i32 s15, s15, s76
	s_cmpk_gt_i32 s6, 0x3ff
	v_lshl_add_u64 v[84:85], v[84:85], 0, s[34:35]
	s_waitcnt vmcnt(3)
	v_lshlrev_b32_e32 v36, 16, v20
	v_and_b32_e32 v37, 0xffff0000, v20
	v_lshlrev_b32_e32 v20, 16, v21
	v_and_b32_e32 v21, 0xffff0000, v21
	v_mul_f32_e32 v23, 0xbfb8aa3b, v36
	v_mul_f32_e32 v38, 0xbfb8aa3b, v37
	v_mul_f32_e32 v39, 0xbfb8aa3b, v20
	v_mul_f32_e32 v40, 0xbfb8aa3b, v21
	v_exp_f32_e32 v23, v23
	v_exp_f32_e32 v38, v38
	v_exp_f32_e32 v39, v39
	v_exp_f32_e32 v40, v40
	v_add_f32_e32 v23, 1.0, v23
	v_add_f32_e32 v41, 1.0, v38
	v_add_f32_e32 v42, 1.0, v39
	v_add_f32_e32 v43, 1.0, v40
	v_rcp_f32_e32 v38, v23
	v_rcp_f32_e32 v39, v41
	v_rcp_f32_e32 v40, v42
	v_rcp_f32_e32 v41, v43
	s_waitcnt vmcnt(2)
	v_pk_mul_f32 v[0:1], v[0:1], v[32:33]
	v_pk_mul_f32 v[2:3], v[2:3], v[18:19]
	v_pk_mul_f32 v[18:19], v[38:39], v[36:37]
	v_pk_mul_f32 v[20:21], v[40:41], v[20:21]
	v_pk_mul_f32 v[0:1], v[0:1], v[18:19]
	v_pk_mul_f32 v[2:3], v[2:3], v[20:21]
	v_cvt_pk_bf16_f32 v0, v0, v1
	v_cvt_pk_bf16_f32 v1, v2, v3
	global_store_dwordx2 v[34:35], v[0:1], off offset:1024
	global_load_dwordx4 v[18:21], v[8:9], off offset:32
	global_load_dwordx2 v[2:3], v[26:27], off offset:32
	v_lshl_add_u64 v[0:1], v[24:25], 0, s[4:5]
	s_waitcnt vmcnt(4)
	v_lshlrev_b32_e32 v24, 16, v30
	v_and_b32_e32 v25, 0xffff0000, v30
	v_lshlrev_b32_e32 v26, 16, v31
	v_and_b32_e32 v27, 0xffff0000, v31
	v_mul_f32_e32 v23, 0xbfb8aa3b, v24
	v_mul_f32_e32 v30, 0xbfb8aa3b, v25
	v_mul_f32_e32 v31, 0xbfb8aa3b, v26
	v_mul_f32_e32 v32, 0xbfb8aa3b, v27
	v_exp_f32_e32 v23, v23
	v_exp_f32_e32 v30, v30
	v_exp_f32_e32 v31, v31
	v_exp_f32_e32 v32, v32
	v_add_f32_e32 v23, 1.0, v23
	v_add_f32_e32 v33, 1.0, v30
	v_add_f32_e32 v34, 1.0, v31
	v_add_f32_e32 v35, 1.0, v32
	v_rcp_f32_e32 v30, v23
	v_rcp_f32_e32 v31, v33
	v_rcp_f32_e32 v32, v34
	v_rcp_f32_e32 v33, v35
	v_pk_mul_f32 v[14:15], v[14:15], v[22:23] op_sel_hi:[1,0]
	v_pk_mul_f32 v[16:17], v[16:17], v[22:23] op_sel_hi:[1,0]
	v_pk_mul_f32 v[24:25], v[30:31], v[24:25]
	v_pk_mul_f32 v[26:27], v[32:33], v[26:27]
	s_waitcnt vmcnt(1)
	v_pk_mul_f32 v[14:15], v[14:15], v[18:19]
	v_pk_mul_f32 v[16:17], v[16:17], v[20:21]
	v_pk_mul_f32 v[14:15], v[14:15], v[24:25]
	v_pk_mul_f32 v[16:17], v[16:17], v[26:27]
	v_cvt_pk_bf16_f32 v14, v14, v15
	v_cvt_pk_bf16_f32 v15, v16, v17
	global_store_dwordx2 v[0:1], v[14:15], off offset:16
	global_load_dwordx4 v[14:17], v[8:9], off offset:64
	s_waitcnt vmcnt(2)
	v_lshlrev_b32_e32 v18, 16, v2
	v_and_b32_e32 v19, 0xffff0000, v2
	v_lshlrev_b32_e32 v2, 16, v3
	v_and_b32_e32 v3, 0xffff0000, v3
	v_mul_f32_e32 v20, 0xbfb8aa3b, v18
	v_mul_f32_e32 v21, 0xbfb8aa3b, v19
	v_mul_f32_e32 v23, 0xbfb8aa3b, v2
	v_mul_f32_e32 v24, 0xbfb8aa3b, v3
	v_exp_f32_e32 v20, v20
	v_exp_f32_e32 v21, v21
	v_exp_f32_e32 v23, v23
	v_exp_f32_e32 v24, v24
	v_add_f32_e32 v20, 1.0, v20
	v_add_f32_e32 v21, 1.0, v21
	v_add_f32_e32 v23, 1.0, v23
	v_add_f32_e32 v25, 1.0, v24
	v_rcp_f32_e32 v20, v20
	v_rcp_f32_e32 v21, v21
	v_rcp_f32_e32 v24, v23
	v_rcp_f32_e32 v25, v25
	v_pk_mul_f32 v[10:11], v[10:11], v[22:23] op_sel_hi:[1,0]
	v_pk_mul_f32 v[12:13], v[12:13], v[22:23] op_sel_hi:[1,0]
	v_pk_mul_f32 v[18:19], v[20:21], v[18:19]
	v_pk_mul_f32 v[2:3], v[24:25], v[2:3]
	v_pk_mul_f32 v[4:5], v[4:5], v[22:23] op_sel_hi:[1,0]
	v_pk_mul_f32 v[6:7], v[6:7], v[22:23] op_sel_hi:[1,0]
	s_waitcnt vmcnt(0)
	v_pk_mul_f32 v[10:11], v[10:11], v[14:15]
	v_pk_mul_f32 v[12:13], v[12:13], v[16:17]
	v_pk_mul_f32 v[10:11], v[10:11], v[18:19]
	v_pk_mul_f32 v[2:3], v[12:13], v[2:3]
	v_cvt_pk_bf16_f32 v10, v10, v11
	v_cvt_pk_bf16_f32 v11, v2, v3
	global_store_dwordx2 v[0:1], v[10:11], off offset:32
	global_load_dwordx4 v[8:11], v[8:9], off offset:96
	v_lshlrev_b32_e32 v2, 16, v28
	v_and_b32_e32 v3, 0xffff0000, v28
	v_lshlrev_b32_e32 v12, 16, v29
	v_and_b32_e32 v13, 0xffff0000, v29
	v_mul_f32_e32 v14, 0xbfb8aa3b, v2
	v_mul_f32_e32 v15, 0xbfb8aa3b, v3
	v_mul_f32_e32 v16, 0xbfb8aa3b, v12
	v_mul_f32_e32 v17, 0xbfb8aa3b, v13
	v_exp_f32_e32 v14, v14
	v_exp_f32_e32 v15, v15
	v_exp_f32_e32 v16, v16
	v_exp_f32_e32 v17, v17
	v_add_f32_e32 v14, 1.0, v14
	v_add_f32_e32 v15, 1.0, v15
	v_add_f32_e32 v16, 1.0, v16
	v_add_f32_e32 v17, 1.0, v17
	v_rcp_f32_e32 v14, v14
	v_rcp_f32_e32 v15, v15
	v_rcp_f32_e32 v16, v16
	v_rcp_f32_e32 v17, v17
	v_pk_mul_f32 v[2:3], v[14:15], v[2:3]
	v_pk_mul_f32 v[12:13], v[16:17], v[12:13]
	s_waitcnt vmcnt(0)
	v_pk_mul_f32 v[4:5], v[4:5], v[8:9]
	v_pk_mul_f32 v[6:7], v[6:7], v[10:11]
	v_pk_mul_f32 v[2:3], v[4:5], v[2:3]
	v_pk_mul_f32 v[4:5], v[6:7], v[12:13]
	v_cvt_pk_bf16_f32 v2, v2, v3
	v_cvt_pk_bf16_f32 v3, v4, v5
	global_store_dwordx2 v[0:1], v[2:3], off offset:48
	s_waitcnt vmcnt(0) lgkmcnt(0)
	s_barrier
	s_cbranch_scc1 .LBB0_583
.LBB0_581:
	s_and_b32 s7, s15, 0xffffffc0
	s_and_b32 s16, s6, 3
	s_and_b32 s17, s15, 0xfc0
	v_add_u32_e32 v2, s7, v89
	v_mov_b64_e32 v[0:1], s[12:13]
	v_mad_i64_i32 v[0:1], s[4:5], v2, s85, v[0:1]
	s_lshl_b32 s26, s16, 8
	v_add_u32_e32 v2, s17, v89
	v_lshl_add_u64 v[0:1], v[0:1], 0, s[26:27]
	v_ashrrev_i32_e32 v3, 31, v2
	v_lshl_add_u64 v[0:1], v[0:1], 0, v[168:169]
	v_lshlrev_b64 v[2:3], 9, v[2:3]
	global_load_dwordx4 v[32:35], v[0:1], off offset:3072
	global_load_dwordx4 v[36:39], v[0:1], off offset:3200
	v_lshl_add_u64 v[2:3], v[80:81], 0, v[2:3]
	v_add_co_u32_e64 v4, s[4:5], s86, v0
	global_load_dwordx4 v[28:31], v[2:3], off
	global_load_dwordx4 v[24:27], v[2:3], off offset:16
	global_load_dwordx4 v[16:19], v[2:3], off offset:32
	global_load_dwordx4 v[8:11], v[2:3], off offset:48
	v_addc_co_u32_e64 v5, s[4:5], 0, v1, s[4:5]
	global_load_dwordx4 v[20:23], v[4:5], off
	global_load_dwordx4 v[12:15], v[4:5], off offset:128
	s_getpc_b64 s[4:5]
	s_add_u32 s4, s4, _ZN2mk5LOG2GE@rel32@lo+4
	s_addc_u32 s5, s5, _ZN2mk5LOG2GE@rel32@hi+12
	s_lshl_b32 s17, s16, 2
	s_load_dword s4, s[4:5], s17 offset:0x0
	global_load_dwordx4 v[0:3], v[4:5], off offset:1024
	s_nop 0
	global_load_dwordx4 v[4:7], v[4:5], off offset:1152
	s_lshl_b32 s16, s16, 7
	s_waitcnt lgkmcnt(0)
	v_mul_f32_e32 v76, s4, v122
	v_exp_f32_e32 v136, v76
	v_mul_f32_e32 v76, s4, v124
	v_exp_f32_e32 v137, v76
	v_mul_f32_e32 v76, s4, v126
	v_mul_f32_e32 v87, s4, v128
	v_exp_f32_e32 v138, v76
	v_exp_f32_e32 v139, v87
	s_waitcnt vmcnt(9)
	v_lshlrev_b32_e32 v40, 16, v32
	v_and_b32_e32 v41, 0xffff0000, v32
	s_waitcnt vmcnt(8)
	v_lshlrev_b32_e32 v42, 16, v36
	v_and_b32_e32 v43, 0xffff0000, v36
	s_waitcnt vmcnt(7)
	v_mov_b32_e32 v44, v28
	v_mov_b32_e32 v45, v30
	v_mov_b32_e32 v30, v29
	v_lshlrev_b32_e32 v28, 16, v33
	v_and_b32_e32 v29, 0xffff0000, v33
	v_lshlrev_b32_e32 v32, 16, v37
	v_and_b32_e32 v33, 0xffff0000, v37
	s_waitcnt vmcnt(6)
	v_mov_b32_e32 v47, v26
	v_mov_b32_e32 v26, v25
	v_lshlrev_b32_e32 v36, 16, v38
	v_and_b32_e32 v37, 0xffff0000, v38
	s_waitcnt vmcnt(5)
	v_mov_b32_e32 v48, v16
	v_mov_b32_e32 v49, v18
	v_mov_b32_e32 v18, v17
	v_mov_b32_e32 v46, v24
	v_lshlrev_b32_e32 v24, 16, v34
	v_and_b32_e32 v25, 0xffff0000, v34
	v_lshlrev_b32_e32 v16, 16, v35
	v_and_b32_e32 v17, 0xffff0000, v35
	v_lshlrev_b32_e32 v34, 16, v39
	v_and_b32_e32 v35, 0xffff0000, v39
	s_waitcnt vmcnt(4)
	v_mov_b32_e32 v50, v8
	v_mov_b32_e32 v51, v10
	v_mov_b32_e32 v10, v9
	v_pk_mul_f32 v[8:9], v[30:31], v[42:43]
	v_pk_mul_f32 v[38:39], v[44:45], v[42:43]
	v_pk_mul_f32 v[42:43], v[26:27], v[32:33]
	v_pk_mul_f32 v[52:53], v[18:19], v[36:37]
	v_pk_mul_f32 v[36:37], v[48:49], v[36:37]
	s_waitcnt vmcnt(2)
	v_lshlrev_b32_e32 v58, 16, v12
	v_and_b32_e32 v59, 0xffff0000, v12
	v_pk_fma_f32 v[8:9], v[44:45], v[40:41], v[8:9] neg_lo:[0,0,1] neg_hi:[0,0,1]
	v_pk_fma_f32 v[38:39], v[30:31], v[40:41], v[38:39]
	v_pk_fma_f32 v[40:41], v[46:47], v[28:29], v[42:43] neg_lo:[0,0,1] neg_hi:[0,0,1]
	v_pk_fma_f32 v[42:43], v[48:49], v[24:25], v[52:53] neg_lo:[0,0,1] neg_hi:[0,0,1]
	v_pk_fma_f32 v[24:25], v[18:19], v[24:25], v[36:37]
	v_lshlrev_b32_e32 v12, 16, v13
	v_and_b32_e32 v13, 0xffff0000, v13
	v_pk_mul_f32 v[32:33], v[46:47], v[32:33]
	v_lshlrev_b32_e32 v56, 16, v20
	v_and_b32_e32 v57, 0xffff0000, v20
	v_cvt_pk_bf16_f32 v36, v38, v39
	v_cvt_pk_bf16_f32 v38, v24, v25
	v_lshlrev_b32_e32 v20, 16, v21
	v_and_b32_e32 v21, 0xffff0000, v21
	v_pk_mul_f32 v[24:25], v[26:27], v[12:13]
	v_pk_mul_f32 v[12:13], v[46:47], v[12:13]
	v_pk_fma_f32 v[28:29], v[26:27], v[28:29], v[32:33]
	v_pk_fma_f32 v[12:13], v[26:27], v[20:21], v[12:13]
	v_lshlrev_b32_e32 v26, 16, v14
	v_and_b32_e32 v27, 0xffff0000, v14
	v_cvt_pk_bf16_f32 v37, v28, v29
	v_pk_fma_f32 v[24:25], v[46:47], v[20:21], v[24:25] neg_lo:[0,0,1] neg_hi:[0,0,1]
	v_pk_mul_f32 v[20:21], v[12:13], s[40:41] op_sel_hi:[1,0]
	v_lshlrev_b32_e32 v12, 16, v22
	v_and_b32_e32 v13, 0xffff0000, v22
	v_pk_mul_f32 v[28:29], v[18:19], v[26:27]
	v_pk_mul_f32 v[26:27], v[48:49], v[26:27]
	v_pk_mul_f32 v[54:55], v[10:11], v[34:35]
	v_pk_mul_f32 v[34:35], v[50:51], v[34:35]
	v_pk_fma_f32 v[28:29], v[48:49], v[12:13], v[28:29] neg_lo:[0,0,1] neg_hi:[0,0,1]
	v_pk_fma_f32 v[12:13], v[18:19], v[12:13], v[26:27]
	v_lshlrev_b32_e32 v14, 16, v15
	v_and_b32_e32 v15, 0xffff0000, v15
	v_pk_fma_f32 v[52:53], v[50:51], v[16:17], v[54:55] neg_lo:[0,0,1] neg_hi:[0,0,1]
	v_pk_fma_f32 v[16:17], v[10:11], v[16:17], v[34:35]
	v_pk_mul_f32 v[54:55], v[30:31], v[58:59]
	v_pk_mul_f32 v[18:19], v[12:13], s[40:41] op_sel_hi:[1,0]
	v_lshlrev_b32_e32 v12, 16, v23
	v_and_b32_e32 v13, 0xffff0000, v23
	v_pk_mul_f32 v[22:23], v[10:11], v[14:15]
	v_cvt_pk_bf16_f32 v32, v8, v9
	v_cvt_pk_bf16_f32 v39, v16, v17
	v_pk_fma_f32 v[8:9], v[44:45], v[56:57], v[54:55] neg_lo:[0,0,1] neg_hi:[0,0,1]
	v_pk_mul_f32 v[16:17], v[44:45], v[58:59]
	v_pk_fma_f32 v[22:23], v[50:51], v[12:13], v[22:23] neg_lo:[0,0,1] neg_hi:[0,0,1]
	v_pk_mul_f32 v[14:15], v[50:51], v[14:15]
	v_pk_mul_f32 v[8:9], v[8:9], s[40:41] op_sel_hi:[1,0]
	v_pk_fma_f32 v[16:17], v[30:31], v[56:57], v[16:17]
	v_pk_mul_f32 v[24:25], v[24:25], s[40:41] op_sel_hi:[1,0]
	v_pk_mul_f32 v[28:29], v[28:29], s[40:41] op_sel_hi:[1,0]
	v_pk_mul_f32 v[22:23], v[22:23], s[40:41] op_sel_hi:[1,0]
	v_pk_fma_f32 v[10:11], v[10:11], v[12:13], v[14:15]
	v_cvt_pk_bf16_f32 v33, v40, v41
	v_cvt_pk_bf16_f32 v34, v42, v43
	v_cvt_pk_bf16_f32 v35, v52, v53
	v_pk_mul_f32 v[16:17], v[16:17], s[40:41] op_sel_hi:[1,0]
	v_pk_mul_f32 v[26:27], v[10:11], s[40:41] op_sel_hi:[1,0]
	v_cvt_pk_bf16_f32 v8, v8, v9
	v_cvt_pk_bf16_f32 v9, v24, v25
	v_cvt_pk_bf16_f32 v10, v28, v29
	v_cvt_pk_bf16_f32 v11, v22, v23
	ds_write_b128 v90, v[32:35]
	ds_write_b128 v90, v[36:39] offset:128
	v_cvt_pk_bf16_f32 v12, v16, v17
	v_cvt_pk_bf16_f32 v13, v20, v21
	v_cvt_pk_bf16_f32 v14, v18, v19
	v_cvt_pk_bf16_f32 v15, v26, v27
	ds_write_b128 v90, v[8:11] offset:17408
	ds_write_b128 v90, v[12:15] offset:17536
	s_waitcnt vmcnt(1)
	ds_write_b128 v90, v[0:3] offset:34816
	s_waitcnt vmcnt(0)
	ds_write_b128 v90, v[4:7] offset:34944
	s_waitcnt vmcnt(0) lgkmcnt(0)
	s_barrier
	ds_read_b128 v[0:3], v91 offset:17408
	ds_read_b128 v[32:35], v94
	ds_read_b128 v[36:39], v91 offset:17440
	ds_read_b128 v[52:55], v94 offset:32
	s_waitcnt lgkmcnt(2)
	v_mfma_f32_32x32x16_bf16 v[16:31], v[0:3], v[32:35], 0
	ds_read_b128 v[0:3], v92 offset:17408
	ds_read_b128 v[40:43], v92 offset:17440
	s_waitcnt lgkmcnt(1)
	v_mfma_f32_32x32x16_bf16 v[0:15], v[0:3], v[32:35], 0
	v_mfma_f32_32x32x16_bf16 v[16:31], v[36:39], v[52:55], v[16:31]
	s_waitcnt lgkmcnt(0)
	v_mfma_f32_32x32x16_bf16 v[0:15], v[40:43], v[52:55], v[0:15]
	ds_read_b128 v[36:39], v91 offset:17472
	ds_read_b128 v[56:59], v94 offset:64
	ds_read_b128 v[40:43], v91 offset:17504
	ds_read_b128 v[60:63], v94 offset:96
	s_waitcnt lgkmcnt(2)
	v_mfma_f32_32x32x16_bf16 v[16:31], v[36:39], v[56:59], v[16:31]
	ds_read_b128 v[36:39], v92 offset:17472
	ds_read_b128 v[44:47], v92 offset:17504
	s_waitcnt lgkmcnt(1)
	v_mfma_f32_32x32x16_bf16 v[0:15], v[36:39], v[56:59], v[0:15]
	v_mfma_f32_32x32x16_bf16 v[16:31], v[40:43], v[60:63], v[16:31]
	ds_read_b128 v[36:39], v91 offset:17536
	ds_read_b128 v[64:67], v94 offset:128
	ds_read_b128 v[40:43], v91 offset:17568
	ds_read_b128 v[68:71], v94 offset:160
	s_waitcnt lgkmcnt(4)
	v_mfma_f32_32x32x16_bf16 v[0:15], v[44:47], v[60:63], v[0:15]
	s_waitcnt lgkmcnt(2)
	v_mfma_f32_32x32x16_bf16 v[16:31], v[36:39], v[64:67], v[16:31]
	ds_read_b128 v[36:39], v92 offset:17536
	ds_read_b128 v[44:47], v92 offset:17568
	s_waitcnt lgkmcnt(1)
	v_mfma_f32_32x32x16_bf16 v[0:15], v[36:39], v[64:67], v[0:15]
	v_mfma_f32_32x32x16_bf16 v[16:31], v[40:43], v[68:71], v[16:31]
	ds_read_b128 v[36:39], v91 offset:17600
	ds_read_b128 v[72:75], v94 offset:192
	ds_read_b128 v[40:43], v91 offset:17632
	ds_read_b128 v[48:51], v94 offset:224
	s_waitcnt lgkmcnt(4)
	v_mfma_f32_32x32x16_bf16 v[0:15], v[44:47], v[68:71], v[0:15]
	s_waitcnt lgkmcnt(2)
	v_mfma_f32_32x32x16_bf16 v[16:31], v[36:39], v[72:75], v[16:31]
	ds_read_b128 v[36:39], v92 offset:17600
	ds_read_b128 v[44:47], v92 offset:17632
	global_load_dwordx4 v[76:79], v[84:85], off offset:-64
	s_waitcnt lgkmcnt(1)
	v_mfma_f32_32x32x16_bf16 v[0:15], v[36:39], v[72:75], v[0:15]
	v_mul_f32_e32 v36, s4, v98
	v_mul_f32_e32 v37, s4, v100
	v_exp_f32_e32 v36, v36
	v_exp_f32_e32 v37, v37
	v_mul_f32_e32 v38, s4, v99
	v_exp_f32_e32 v38, v38
	v_mfma_f32_32x32x16_bf16 v[16:31], v[40:43], v[48:51], v[16:31]
	s_waitcnt lgkmcnt(0)
	v_mfma_f32_32x32x16_bf16 v[0:15], v[44:47], v[48:51], v[0:15]
	s_nop 9
	v_mul_f32_e64 v16, v36, v16
	v_mul_f32_e64 v17, v37, v17
	v_mul_f32_e32 v36, s4, v101
	v_exp_f32_e32 v39, v36
	v_mul_f32_e32 v36, s4, v102
	v_exp_f32_e32 v40, v36
	v_mul_f32_e32 v36, s4, v104
	v_exp_f32_e32 v41, v36
	v_pk_mul_f32 v[36:37], v[38:39], v[0:1]
	v_mul_f32_e32 v0, s4, v103
	v_mul_f32_e32 v1, s4, v105
	v_exp_f32_e32 v0, v0
	v_exp_f32_e32 v1, v1
	v_mul_f32_e32 v38, s4, v106
	v_pk_mul_f32 v[18:19], v[40:41], v[18:19]
	v_exp_f32_e32 v40, v38
	v_mul_f32_e32 v38, s4, v108
	v_exp_f32_e32 v41, v38
	v_pk_mul_f32 v[38:39], v[0:1], v[2:3]
	v_mul_f32_e32 v0, s4, v107
	v_mul_f32_e32 v1, s4, v109
	v_exp_f32_e32 v0, v0
	v_exp_f32_e32 v1, v1
	v_mul_f32_e32 v2, s4, v110
	v_exp_f32_e32 v42, v2
	v_mul_f32_e32 v2, s4, v111
	v_exp_f32_e32 v44, v2
	v_mul_f32_e32 v2, s4, v112
	v_exp_f32_e32 v43, v2
	v_mul_f32_e32 v2, s4, v113
	v_pk_mul_f32 v[20:21], v[40:41], v[20:21]
	v_exp_f32_e32 v45, v2
	v_pk_mul_f32 v[40:41], v[0:1], v[4:5]
	global_load_dwordx4 v[0:3], v[84:85], off offset:-128
	v_mul_f32_e32 v4, s4, v114
	v_pk_mul_f32 v[46:47], v[42:43], v[22:23]
	v_exp_f32_e32 v22, v4
	v_mul_f32_e32 v4, s4, v116
	v_pk_mul_f32 v[42:43], v[44:45], v[6:7]
	v_exp_f32_e32 v23, v4
	global_load_dwordx4 v[4:7], v[84:85], off offset:-96
	v_mul_f32_e32 v44, s4, v118
	v_mul_f32_e32 v45, s4, v120
	v_exp_f32_e32 v44, v44
	v_exp_f32_e32 v45, v45
	v_pk_mul_f32 v[140:141], v[22:23], v[24:25]
	v_pk_mul_f32 v[144:145], v[136:137], v[28:29]
	v_pk_mul_f32 v[146:147], v[138:139], v[30:31]
	v_pk_mul_f32 v[142:143], v[44:45], v[26:27]
	ds_read_u16 v22, v130 offset:34816
	ds_read_u16 v23, v130 offset:35088
	ds_read_u16 v45, v130 offset:39712
	ds_read_u16 v87, v130 offset:39984
	ds_read_u16 v136, v130 offset:41344
	ds_read_u16 v137, v130 offset:41616
	ds_read_u16 v138, v130 offset:41888
	ds_read_u16 v139, v130 offset:42160
	s_waitcnt lgkmcnt(6)
	v_lshl_or_b32 v22, v23, 16, v22
	ds_read_u16 v23, v131 offset:34816
	ds_read_u16 v24, v131 offset:35088
	ds_read_u16 v25, v132 offset:34816
	ds_read_u16 v26, v132 offset:35088
	ds_read_u16 v27, v133 offset:34816
	ds_read_u16 v28, v133 offset:35088
	ds_read_u16 v44, v134 offset:34816
	ds_read_u16 v148, v134 offset:35088
	s_waitcnt lgkmcnt(6)
	v_lshl_or_b32 v23, v24, 16, v23
	s_waitcnt lgkmcnt(4)
	v_lshl_or_b32 v24, v26, 16, v25
	s_waitcnt lgkmcnt(2)
	v_lshl_or_b32 v25, v28, 16, v27
	v_cvt_pk_bf16_f32 v16, v16, v17
	v_cvt_pk_bf16_f32 v17, v18, v19
	v_cvt_pk_bf16_f32 v18, v20, v21
	v_cvt_pk_bf16_f32 v19, v46, v47
	s_waitcnt lgkmcnt(0)
	v_lshl_or_b32 v44, v148, 16, v44
	v_lshl_or_b32 v45, v87, 16, v45
	v_mfma_f32_32x32x16_bf16 v[16:31], v[22:25], v[16:19], 0
	v_lshl_or_b32 v46, v137, 16, v136
	v_lshl_or_b32 v47, v139, 16, v138
	v_cvt_pk_bf16_f32 v136, v140, v141
	v_cvt_pk_bf16_f32 v137, v142, v143
	v_cvt_pk_bf16_f32 v138, v144, v145
	v_cvt_pk_bf16_f32 v139, v146, v147
	v_cvt_pk_bf16_f32 v36, v36, v37
	v_cvt_pk_bf16_f32 v37, v38, v39
	v_mfma_f32_32x32x16_bf16 v[16:31], v[44:47], v[136:139], v[16:31]
	ds_read_u16 v44, v130 offset:43520
	ds_read_u16 v45, v130 offset:43792
	ds_read_u16 v46, v130 offset:44064
	ds_read_u16 v47, v130 offset:44336
	ds_read_u16 v87, v130 offset:45696
	ds_read_u16 v140, v130 offset:45968
	ds_read_u16 v141, v130 offset:46240
	ds_read_u16 v142, v130 offset:46512
	global_load_dwordx4 v[136:139], v[84:85], off offset:-32
	s_waitcnt lgkmcnt(6)
	v_lshl_or_b32 v44, v45, 16, v44
	s_waitcnt lgkmcnt(4)
	v_lshl_or_b32 v45, v47, 16, v46
	s_waitcnt lgkmcnt(2)
	v_lshl_or_b32 v46, v140, 16, v87
	s_waitcnt lgkmcnt(0)
	v_lshl_or_b32 v47, v142, 16, v141
	global_load_dwordx4 v[140:143], v[84:85], off
	v_cvt_pk_bf16_f32 v38, v40, v41
	v_cvt_pk_bf16_f32 v39, v42, v43
	s_nop 1
	v_mfma_f32_32x32x16_bf16 v[16:31], v[44:47], v[36:39], v[16:31]
	s_waitcnt vmcnt(3)
	v_mfma_f32_32x32x16_bf16 v[32:47], v[0:3], v[32:35], 0
	global_load_dwordx4 v[0:3], v[84:85], off offset:32
	s_waitcnt vmcnt(3)
	v_mfma_f32_32x32x16_bf16 v[32:47], v[4:7], v[52:55], v[32:47]
	global_load_dwordx4 v[4:7], v[84:85], off offset:64
	global_load_dwordx4 v[52:55], v[84:85], off offset:96
	v_mfma_f32_32x32x16_bf16 v[32:47], v[76:79], v[56:59], v[32:47]
	v_mul_f32_e32 v56, s4, v115
	v_mul_f32_e32 v57, s4, v117
	v_mul_f32_e32 v58, s4, v119
	v_mul_f32_e32 v59, s4, v121
	v_exp_f32_e32 v56, v56
	v_exp_f32_e32 v57, v57
	v_exp_f32_e32 v58, v58
	s_waitcnt vmcnt(4)
	v_mfma_f32_32x32x16_bf16 v[32:47], v[136:139], v[60:63], v[32:47]
	v_exp_f32_e32 v59, v59
	v_mul_f32_e32 v60, s4, v123
	v_mul_f32_e32 v61, s4, v125
	v_mul_f32_e32 v62, s4, v127
	v_mul_f32_e32 v63, s4, v129
	v_exp_f32_e32 v60, v60
	v_exp_f32_e32 v61, v61
	s_waitcnt vmcnt(3)
	v_mfma_f32_32x32x16_bf16 v[32:47], v[140:143], v[64:67], v[32:47]
	v_exp_f32_e32 v62, v62
	v_exp_f32_e32 v63, v63
	s_waitcnt vmcnt(2)
	v_mfma_f32_32x32x16_bf16 v[32:47], v[0:3], v[68:71], v[32:47]
	v_mul_f32_e64 v0, v56, v8
	v_mul_f32_e64 v1, v57, v9
	v_mul_f32_e64 v2, v58, v10
	v_mul_f32_e64 v3, v59, v11
	v_mul_f32_e64 v8, v60, v12
	v_mul_f32_e64 v9, v61, v13
	v_pk_mul_f32 v[10:11], v[62:63], v[14:15]
	v_cvt_pk_bf16_f32 v0, v0, v1
	v_cvt_pk_bf16_f32 v1, v2, v3
	s_waitcnt vmcnt(1)
	v_mfma_f32_32x32x16_bf16 v[32:47], v[4:7], v[72:75], v[32:47]
	ds_read_u16 v2, v130 offset:47872
	ds_read_u16 v3, v130 offset:48144
	ds_read_u16 v5, v130 offset:48416
	ds_read_u16 v6, v130 offset:48688
	ds_read_u16 v7, v130 offset:50048
	ds_read_u16 v12, v130 offset:50320
	ds_read_u16 v13, v130 offset:50592
	ds_read_u16 v14, v130 offset:50864
	s_waitcnt lgkmcnt(6)
	v_lshl_or_b32 v4, v3, 16, v2
	s_waitcnt lgkmcnt(4)
	v_lshl_or_b32 v5, v6, 16, v5
	s_waitcnt lgkmcnt(2)
	v_lshl_or_b32 v6, v12, 16, v7
	v_cvt_pk_bf16_f32 v2, v8, v9
	s_waitcnt lgkmcnt(0)
	v_lshl_or_b32 v7, v14, 16, v13
	v_cvt_pk_bf16_f32 v3, v10, v11
	s_waitcnt vmcnt(0)
	v_mfma_f32_32x32x16_bf16 v[32:47], v[52:55], v[48:51], v[32:47]
	v_mul_f32_e32 v8, s4, v95
	v_exp_f32_e32 v8, v8
	v_mfma_f32_32x32x16_bf16 v[16:31], v[4:7], v[0:3], v[16:31]
	s_nop 11
	v_pk_fma_f32 v[32:33], v[8:9], v[32:33], v[16:17] op_sel_hi:[0,1,1]
	v_pk_mul_f32 v[0:1], v[32:33], v[32:33]
	v_pk_fma_f32 v[18:19], v[8:9], v[34:35], v[18:19] op_sel_hi:[0,1,1]
	v_pk_mul_f32 v[2:3], v[18:19], v[18:19]
	v_add_f32_e32 v0, v0, v1
	v_pk_fma_f32 v[14:15], v[8:9], v[36:37], v[20:21] op_sel_hi:[0,1,1]
	v_add_f32_e32 v0, v2, v0
	v_pk_mul_f32 v[20:21], v[14:15], v[14:15]
	v_add_f32_e32 v0, v3, v0
	v_pk_fma_f32 v[16:17], v[8:9], v[38:39], v[22:23] op_sel_hi:[0,1,1]
	v_add_f32_e32 v0, v20, v0
	v_pk_mul_f32 v[22:23], v[16:17], v[16:17]
	v_add_f32_e32 v0, v21, v0
	v_pk_fma_f32 v[10:11], v[8:9], v[40:41], v[24:25] op_sel_hi:[0,1,1]
	v_add_f32_e32 v0, v22, v0
	v_pk_mul_f32 v[24:25], v[10:11], v[10:11]
	v_add_f32_e32 v0, v23, v0
	v_pk_fma_f32 v[12:13], v[8:9], v[42:43], v[26:27] op_sel_hi:[0,1,1]
	v_add_f32_e32 v0, v24, v0
	v_pk_mul_f32 v[26:27], v[12:13], v[12:13]
	v_add_f32_e32 v0, v25, v0
	v_pk_fma_f32 v[4:5], v[8:9], v[44:45], v[28:29] op_sel_hi:[0,1,1]
	v_add_f32_e32 v0, v26, v0
	v_pk_mul_f32 v[28:29], v[4:5], v[4:5]
	v_add_f32_e32 v0, v27, v0
	v_and_b32_e32 v2, 64, v254
	v_pk_fma_f32 v[6:7], v[8:9], v[46:47], v[30:31] op_sel_hi:[0,1,1]
	v_add_f32_e32 v0, v28, v0
	v_xor_b32_e32 v1, 32, v254
	v_add_u32_e32 v2, 64, v2
	v_pk_mul_f32 v[8:9], v[6:7], v[6:7]
	v_add_f32_e32 v0, v29, v0
	v_cmp_lt_i32_e64 s[4:5], v1, v2
	v_add_f32_e32 v0, v8, v0
	v_add_f32_e32 v0, v9, v0
	v_cndmask_b32_e64 v1, v254, v1, s[4:5]
	v_lshlrev_b32_e32 v1, 2, v1
	ds_bpermute_b32 v1, v1, v0
	s_and_saveexec_b64 s[4:5], vcc
	s_cbranch_execz .LBB0_580
	s_waitcnt lgkmcnt(0)
	v_add_f32_e32 v0, v0, v1
	ds_write_b32 v135, v0 offset:52224
	s_branch .LBB0_580
